# v18 + nt hint on the HGRN2 sample-state streams (read-once input states, write-once output states) in P2
# speedup vs baseline: 1.0394x; 1.0394x over previous
; #define LAS __attribute__((address_space(3)))
; #define STAMP(i) do { if (F.bid == AMP_BLK && F.tid == 0) { const unsigned long long t_ = __builtin_amdgcn_s_memrealtime(); volatile LAS unsigned* M_ = (volatile LAS unsigned*)(F.lds + LDS_BYTES - 512); M_[64 + 2 * (i)] = (unsigned)t_; M_[65 + 2 * (i)] = (unsigned)(t_ >> 32); } } while (0)
; #define STAMP(i) do { } while (0)
; __device__ __forceinline__ void hgrn_sample_loop(Frame& F) {
;     const int tid = F.tid;
;     LAS float* Qs = (LAS float*)(F.lds + LX_Q); LAS float* K2 = (LAS float*)(F.lds + LX_K2); LAS float* QT = (LAS float*)(F.lds + LX_QT); LAS float* K3T = (LAS float*)(F.lds + LX_K3T); LAS float* Vs = (LAS float*)(F.lds + LX_V);
;     LAS float* DEC = (LAS float*)(F.lds + LX_DEC); LAS float* ATT = (LAS float*)(F.lds + LX_ATT); LAS float* OP = (LAS float*)(F.lds + LX_OP); LAS float* OT = (LAS float*)(F.lds + LX_OT);
;     const bf16* PB = (const bf16*)(F.ws + WS_PB); const float* FZ = (const float*)(F.ws + WS_FZ); bf16* MIX = (bf16*)(F.ws + WS_MIX);
;     const int v4 = (tid & 31) * 4, kg = tid >> 5;
;     int idx = F.bid; if (idx >= SB_B * HH) return;
; __global__ void __launch_bounds__(NWAVES * 64, 2) mk_fwd(Args args) {
;     ...
;     if (IN(2)) {
;         const int nper = (1024 + F.G - 1) / F.G, rot = F.bid % 3;
;         STAMP(30);
;         if (rot == 0) {
;             STAMP(4);
;             for (int it = F.bid; it < 256; it += F.G) s5_item(F, it);
;             STAMP(5);
;             hgA_loop(F, 0, nper);
;             STAMP(6);
;             hgrn_sample_loop(F);
;             STAMP(7);
;         } else if (rot == 1) {
;             hgrn_sample_loop(F);
;             hgA_loop(F, 0, nper);
;             __syncthreads();
;             for (int it = F.bid; it < 256; it += F.G) s5_item(F, it);
;         } else {
;             hgA_loop(F, 0, nper);
;             __syncthreads();
;             for (int it = F.bid; it < 256; it += F.G) s5_item(F, it);
;             hgrn_sample_loop(F);
;         }
.LBB0_274:
	v_readlane_b32 s0, v238, 0
	v_readlane_b32 s1, v238, 1
	s_cmp_lt_i32 s0, 3
	s_cselect_b64 s[0:1], -1, 0
	s_add_u32 s6, s50, 0xa300000
	s_addc_u32 s7, s51, 0
	v_writelane_b32 v238, s6, 47
	s_and_b64 s[0:1], s[0:1], s[4:5]
	s_nop 0
	v_writelane_b32 v238, s7, 48
	v_writelane_b32 v238, s0, 49
	s_andn2_b64 vcc, exec, s[0:1]
	s_nop 0
	v_writelane_b32 v238, s1, 50
	s_cbranch_vccnz .LBB0_551
	s_abs_i32 s0, s52
	v_cvt_f32_u32_e32 v2, s0
	s_sub_i32 s4, 0, s0
	s_add_i32 s3, s52, 0x3ff
	s_ashr_i32 s1, s3, 31
	v_rcp_iflag_f32_e32 v2, v2
	s_abs_i32 s3, s3
	s_ashr_i32 s53, s52, 31
	s_xor_b32 s1, s1, s53
	v_mul_f32_e32 v2, 0x4f7ffffe, v2
	v_cvt_u32_f32_e32 v2, v2
	s_nop 0
	v_readfirstlane_b32 s5, v2
	s_mul_i32 s4, s4, s5
	s_mul_hi_u32 s4, s5, s4
	s_add_i32 s5, s5, s4
	s_mul_hi_u32 s4, s3, s5
	s_mul_i32 s5, s4, s0
	s_sub_i32 s3, s3, s5
	s_add_i32 s5, s4, 1
	s_sub_i32 s6, s3, s0
	s_cmp_ge_u32 s3, s0
	s_cselect_b32 s4, s5, s4
	s_cselect_b32 s3, s6, s3
	s_add_i32 s5, s4, 1
	s_cmp_ge_u32 s3, s0
	s_cselect_b32 s0, s5, s4
	s_xor_b32 s0, s0, s1
	s_sub_i32 s0, s0, s1
	v_writelane_b32 v238, s0, 51
	s_mul_hi_i32 s0, s2, 0x55555556
	s_lshr_b32 s1, s0, 31
	s_add_i32 s0, s0, s1
	s_mul_i32 s0, s0, 3
	s_sub_i32 s0, s2, s0
	s_mov_b64 s[4:5], -1
	v_writelane_b32 v238, s0, 52
	s_cmp_lt_i32 s0, 1
	s_mov_b64 s[0:1], 0
	v_writelane_b32 v238, s96, 53
	s_cbranch_scc1 .LBB0_290
	v_readlane_b32 s0, v238, 52
	s_cmp_eq_u32 s0, 1
	s_mov_b64 s[0:1], -1
	s_cbranch_scc0 .LBB0_372
	s_cmpk_lt_i32 s2, 0x200
	s_cbranch_scc0 .LBB0_293
; #define GAS __attribute__((address_space(1)))
; __device__ __forceinline__ void hgrn_sample_loop(Frame& F) {
;     ...
;     const int v4 = (tid & 31) * 4, kg = tid >> 5;
;     int idx = F.bid; if (idx >= SB_B * HH) return;
;     f32x4 s0[8];
; #pragma unroll
;     for (int j = 0; j < 8; ++j) s0[j] = *(const GAS f32x4*)(F.in[4] + (size_t)idx * HD * HD + (size_t)(8 * kg + j) * HD + v4);
	s_ashr_i32 s3, s2, 31
	v_readlane_b32 s60, v238, 4
	v_lshrrev_b32_e32 v36, 5, v0
	s_lshl_b64 s[4:5], s[2:3], 16
	v_readlane_b32 s68, v238, 12
	v_lshlrev_b32_e32 v4, 3, v36
	v_mov_b32_e32 v135, 0
	v_readlane_b32 s69, v238, 13
	s_add_u32 s0, s68, s4
	v_lshlrev_b32_e32 v6, 4, v0
	v_or_b32_e32 v37, 1, v4
	v_or_b32_e32 v38, 2, v4
	v_or_b32_e32 v39, 3, v4
	v_or_b32_e32 v40, 4, v4
	v_or_b32_e32 v41, 5, v4
	v_or_b32_e32 v42, 6, v4
	v_or_b32_e32 v43, 7, v4
	s_addc_u32 s1, s69, s5
	v_and_b32_e32 v34, 0x1f0, v6
	v_mov_b32_e32 v35, v135
	v_lshlrev_b32_e32 v132, 12, v36
	v_mov_b32_e32 v133, v135
	v_lshlrev_b32_e32 v134, 9, v37
	v_lshlrev_b32_e32 v18, 9, v38
	v_mov_b32_e32 v19, v135
	v_lshlrev_b32_e32 v20, 9, v39
	v_mov_b32_e32 v21, v135
	v_lshlrev_b32_e32 v10, 9, v40
	v_mov_b32_e32 v11, v135
	v_lshlrev_b32_e32 v12, 9, v41
	v_mov_b32_e32 v13, v135
	v_lshlrev_b32_e32 v2, 9, v42
	v_mov_b32_e32 v3, v135
	v_lshlrev_b32_e32 v4, 9, v43
	v_mov_b32_e32 v5, v135
	v_lshl_add_u64 v[26:27], s[0:1], 0, v[34:35]
	v_lshl_add_u64 v[4:5], v[26:27], 0, v[4:5]
	v_lshl_add_u64 v[6:7], v[26:27], 0, v[2:3]
	v_lshl_add_u64 v[12:13], v[26:27], 0, v[12:13]
	v_lshl_add_u64 v[14:15], v[26:27], 0, v[10:11]
	v_lshl_add_u64 v[20:21], v[26:27], 0, v[20:21]
	v_lshl_add_u64 v[22:23], v[26:27], 0, v[18:19]
	v_lshl_add_u64 v[28:29], v[26:27], 0, v[134:135]
	v_lshl_add_u64 v[30:31], v[26:27], 0, v[132:133]
	global_load_dwordx4 v[2:5], v[4:5], off nt
	s_nop 0
	global_load_dwordx4 v[6:9], v[6:7], off nt
	s_nop 0
	global_load_dwordx4 v[10:13], v[12:13], off nt
	s_nop 0
	global_load_dwordx4 v[14:17], v[14:15], off nt
	s_nop 0
	global_load_dwordx4 v[18:21], v[20:21], off nt
	s_nop 0
	global_load_dwordx4 v[22:25], v[22:23], off nt
	s_nop 0
	global_load_dwordx4 v[26:29], v[28:29], off nt
	s_nop 0
	global_load_dwordx4 v[30:33], v[30:31], off nt
	v_and_b32_e32 v44, 7, v0
	v_lshrrev_b32_e32 v45, 6, v0
	v_bfe_u32 v46, v0, 3, 3
	v_lshlrev_b32_e32 v47, 9, v45
	v_lshlrev_b32_e32 v48, 2, v44
	v_add3_u32 v148, 0, v47, v48
	v_lshlrev_b32_e32 v47, 9, v46
	v_add3_u32 v149, 0, v47, v48
	v_mbcnt_lo_u32_b32 v47, -1, 0
	v_mbcnt_hi_u32_b32 v47, -1, v47
	s_movk_i32 s0, 0x80
	v_and_b32_e32 v49, 64, v47
	v_subrev_co_u32_e32 v134, vcc, s0, v0
	v_xor_b32_e32 v48, 1, v47
	v_add_u32_e32 v49, 64, v49
	s_xor_b64 s[10:11], vcc, -1
	v_cmp_lt_i32_e32 vcc, v48, v49
	v_add_u32_e32 v131, 0, v34
	v_lshrrev_b32_e32 v34, 3, v0
	v_cndmask_b32_e32 v48, v47, v48, vcc
	v_lshlrev_b32_e32 v150, 2, v48
	v_xor_b32_e32 v48, 2, v47
	v_cmp_lt_i32_e32 vcc, v48, v49
	v_lshl_add_u32 v153, v34, 2, 0
	v_and_b32_e32 v130, 0x7f, v0
	v_cndmask_b32_e32 v48, v47, v48, vcc
	v_lshlrev_b32_e32 v151, 2, v48
	v_xor_b32_e32 v48, 4, v47
	v_cmp_lt_i32_e32 vcc, v48, v49
	v_xor_b32_e32 v34, 8, v47
	v_cmp_eq_u32_e64 s[6:7], 0, v44
	v_cndmask_b32_e32 v48, v47, v48, vcc
	v_lshl_add_u32 v155, v130, 2, 0
	v_cmp_lt_i32_e32 vcc, v34, v49
	v_lshl_add_u32 v159, v36, 8, 0
	v_mul_i32_i24_e32 v44, 0xffffff20, v36
	v_and_b32_e32 v36, 0x180, v0
	v_cndmask_b32_e32 v34, v47, v34, vcc
	v_lshl_add_u32 v167, v36, 2, v155
	v_lshrrev_b32_e32 v36, 2, v0
	v_readlane_b32 s12, v238, 29
	v_lshlrev_b32_e32 v156, 2, v34
	v_xor_b32_e32 v34, 16, v47
	v_lshl_add_u32 v161, v38, 5, 0
	v_and_b32_e32 v38, 0x60, v36
	s_movk_i32 s3, 0x380
	v_mov_b32_e32 v36, 0x200
	v_readlane_b32 s13, v238, 30
	s_add_i32 s12, s2, s52
	v_cmp_lt_i32_e32 vcc, v34, v49
	v_bitop3_b32 v36, v0, s3, v36 bitop3:0xc8
	s_lshl_b32 s3, s96, 9
	s_ashr_i32 s13, s12, 31
	v_cndmask_b32_e32 v34, v47, v34, vcc
	s_add_i32 s3, s3, 0
	s_lshl_b64 s[12:13], s[12:13], 16
	v_lshlrev_b32_e32 v157, 2, v34
	v_xor_b32_e32 v34, 32, v47
	s_add_u32 s12, s68, s12
	v_cmp_lt_i32_e32 vcc, v34, v49
	v_lshl_add_u32 v169, v36, 2, v155
	v_lshlrev_b32_e32 v36, 3, v154
	s_addc_u32 s13, s69, s13
	v_cndmask_b32_e32 v34, v47, v34, vcc
	v_add_u32_e32 v171, s3, v36
	v_lshl_add_u64 v[140:141], s[12:13], 0, v[132:133]
	s_lshl_b64 s[12:13], s[52:53], 16
	s_lshl_b32 s3, s2, 1
	s_lshl_b32 s33, s52, 1
	v_lshlrev_b32_e32 v158, 2, v34
	v_or_b32_e32 v34, 0x200, v0
	v_lshl_add_u32 v160, v37, 5, 0
	v_mov_b32_e32 v37, v135
	v_readlane_b32 s14, v238, 31
	v_readlane_b32 s15, v238, 32
	s_add_u32 s4, s48, s4
	v_lshl_add_u32 v146, v0, 2, 0
	v_lshrrev_b32_e32 v34, 2, v34
	v_lshl_add_u64 v[136:137], s[14:15], 0, v[36:37]
	v_and_b32_e32 v36, 31, v0
	s_addc_u32 s5, s49, s5
	s_movk_i32 s0, 0x100
	v_mad_u32_u24 v147, v0, 28, v146
	v_mul_i32_i24_e32 v35, 0xffffffe4, v0
	v_lshl_add_u32 v162, v39, 5, 0
	v_and_b32_e32 v39, 0xe0, v34
	v_lshlrev_b32_e32 v34, 1, v154
	v_lshlrev_b32_e32 v138, 4, v36
	v_lshl_add_u64 v[36:37], s[4:5], 0, v[132:133]
	s_mov_b64 s[4:5], 0x4820800
	v_cmp_gt_u32_e64 s[0:1], s0, v0
	v_lshlrev_b32_e32 v152, 2, v48
	v_cmp_gt_u32_e64 s[8:9], v46, v45
	v_lshl_add_u32 v163, v40, 5, 0
	v_lshl_add_u32 v164, v41, 5, 0
	v_lshl_add_u32 v165, v42, 5, 0
	v_lshl_add_u32 v166, v43, 5, 0
	v_add_u32_e32 v168, 0x6300, v167
	v_add_u32_e32 v170, 0x6300, v169
	v_mov_b32_e32 v139, v135
	v_lshl_add_u64 v[142:143], v[36:37], 0, s[4:5]
	v_lshlrev_b64 v[144:145], 1, v[134:135]
	v_add_u32_e32 v133, v147, v35
	v_add_u32_e32 v172, v159, v44
	v_add_u32_e32 v173, 0, v38
	v_add_u32_e32 v174, 0, v39
	v_lshlrev_b32_e32 v134, 1, v34
	v_mov_b32_e32 v175, 0x358637bd
	s_mov_b32 s34, s2
	v_readlane_b32 s61, v238, 5
	v_readlane_b32 s62, v238, 6
	v_readlane_b32 s63, v238, 7
	v_readlane_b32 s64, v238, 8
	v_readlane_b32 s65, v238, 9
	v_readlane_b32 s66, v238, 10
	v_readlane_b32 s67, v238, 11
	v_readlane_b32 s70, v238, 14
	v_readlane_b32 s71, v238, 15
	v_readlane_b32 s72, v238, 16
	v_readlane_b32 s73, v238, 17
	v_readlane_b32 s74, v238, 18
	v_readlane_b32 s75, v238, 19
	v_readlane_b32 s16, v238, 33
	v_readlane_b32 s17, v238, 34
	v_readlane_b32 s18, v238, 35
	v_readlane_b32 s19, v238, 36
	v_readlane_b32 s20, v238, 37
	v_readlane_b32 s21, v238, 38
	v_readlane_b32 s22, v238, 39
	v_readlane_b32 s23, v238, 40
	v_readlane_b32 s24, v238, 41
	v_readlane_b32 s25, v238, 42
	v_readlane_b32 s26, v238, 43
	v_readlane_b32 s27, v238, 44
	s_branch .LBB0_280

; #define GAS __attribute__((address_space(1)))
; #define LAS __attribute__((address_space(3)))
; __device__ __forceinline__ void hgrn_sample_loop(Frame& F) {
;     ...
;         f32x4 vr[8], o[8];
; #pragma unroll
;         for (int t = 0; t < 8; ++t) { vr[t] = *(const LAS f32x4*)(Vs + t * 128 + v4); o[t] = (f32x4){0.f, 0.f, 0.f, 0.f}; }
; #pragma unroll
;         for (int j = 0; j < 8; ++j) { const int k = 8 * kg + j; const f32x4 sv = s0[j]; const f32x4 qa = *(const LAS f32x4*)(QT + k * 8), qb = *(const LAS f32x4*)(QT + k * 8 + 4), ka = *(const LAS f32x4*)(K3T + k * 8), kb = *(const LAS f32x4*)(K3T + k * 8 + 4);
;             f32x4 sn = sv * DEC[k];
;             o[0] += sv * qa.x; o[1] += sv * qa.y; o[2] += sv * qa.z; o[3] += sv * qa.w; o[4] += sv * qb.x; o[5] += sv * qb.y; o[6] += sv * qb.z; o[7] += sv * qb.w;
;             sn += vr[0] * ka.x; sn += vr[1] * ka.y; sn += vr[2] * ka.z; sn += vr[3] * ka.w; sn += vr[4] * kb.x; sn += vr[5] * kb.y; sn += vr[6] * kb.z; sn += vr[7] * kb.w;
;             *(GAS f32x4*)(Sout + (size_t)k * HD + v4) = sn; }
.LBB0_288:
	s_or_b64 exec, exec, s[14:15]
	ds_read_b128 v[62:65], v131 offset:16384
	ds_read_b128 v[58:61], v131 offset:16896
	ds_read_b128 v[54:57], v131 offset:17408
	ds_read_b128 v[50:53], v131 offset:17920
	ds_read_b128 v[46:49], v131 offset:18432
	ds_read_b128 v[42:45], v131 offset:18944
	ds_read_b128 v[38:41], v131 offset:19456
	s_waitcnt lgkmcnt(7)
	ds_read_b128 v[34:37], v131 offset:19968
	ds_read_b128 v[90:93], v172 offset:20480
	ds_read_b128 v[70:73], v159 offset:8192
	ds_read_b128 v[66:69], v159 offset:8208
	ds_read_b128 v[74:77], v159 offset:12288
	ds_read_b128 v[78:81], v159 offset:12304
	ds_read_b128 v[176:179], v172 offset:20496
	s_waitcnt lgkmcnt(5)
	v_pk_mul_f32 v[82:83], v[32:33], v[90:91] op_sel_hi:[1,0]
	v_pk_mul_f32 v[84:85], v[30:31], v[90:91] op_sel_hi:[1,0]
	s_waitcnt lgkmcnt(2)
	v_pk_fma_f32 v[82:83], v[64:65], v[74:75], v[82:83] op_sel_hi:[1,0,1]
	v_pk_fma_f32 v[84:85], v[62:63], v[74:75], v[84:85] op_sel_hi:[1,0,1]
	v_pk_fma_f32 v[82:83], v[60:61], v[74:75], v[82:83] op_sel:[0,1,0]
	v_pk_fma_f32 v[74:75], v[58:59], v[74:75], v[84:85] op_sel:[0,1,0]
	v_pk_fma_f32 v[82:83], v[56:57], v[76:77], v[82:83] op_sel_hi:[1,0,1]
	v_pk_fma_f32 v[74:75], v[54:55], v[76:77], v[74:75] op_sel_hi:[1,0,1]
	v_mov_b32_e32 v76, v77
	v_pk_fma_f32 v[82:83], v[52:53], v[76:77], v[82:83] op_sel_hi:[1,0,1]
	v_pk_fma_f32 v[74:75], v[50:51], v[76:77], v[74:75] op_sel_hi:[1,0,1]
	s_waitcnt lgkmcnt(1)
	v_pk_fma_f32 v[76:77], v[48:49], v[78:79], v[82:83] op_sel_hi:[1,0,1]
	v_pk_fma_f32 v[74:75], v[46:47], v[78:79], v[74:75] op_sel_hi:[1,0,1]
	v_pk_fma_f32 v[76:77], v[44:45], v[78:79], v[76:77] op_sel:[0,1,0]
	v_pk_fma_f32 v[74:75], v[42:43], v[78:79], v[74:75] op_sel:[0,1,0]
	v_pk_fma_f32 v[76:77], v[40:41], v[80:81], v[76:77] op_sel_hi:[1,0,1]
	v_pk_fma_f32 v[74:75], v[38:39], v[80:81], v[74:75] op_sel_hi:[1,0,1]
	v_mov_b32_e32 v78, v81
	v_pk_fma_f32 v[76:77], v[36:37], v[78:79], v[76:77] op_sel_hi:[1,0,1]
	v_pk_fma_f32 v[74:75], v[34:35], v[78:79], v[74:75] op_sel_hi:[1,0,1]
	v_lshl_add_u64 v[188:189], v[142:143], 0, v[138:139]
	global_store_dwordx4 v[188:189], v[74:77], off offset:-2048 nt
	ds_read_b128 v[78:81], v160 offset:12288
	ds_read_b128 v[86:89], v160 offset:8192
	ds_read_b128 v[74:77], v160 offset:8208
	ds_read_b128 v[82:85], v160 offset:12304
	v_pk_mul_f32 v[94:95], v[28:29], v[90:91] op_sel:[0,1]
	v_pk_mul_f32 v[90:91], v[26:27], v[90:91] op_sel:[0,1]
	s_waitcnt lgkmcnt(3)
	v_pk_fma_f32 v[94:95], v[64:65], v[78:79], v[94:95] op_sel_hi:[1,0,1]
	v_pk_fma_f32 v[90:91], v[62:63], v[78:79], v[90:91] op_sel_hi:[1,0,1]
	v_pk_fma_f32 v[94:95], v[60:61], v[78:79], v[94:95] op_sel:[0,1,0]
	v_pk_fma_f32 v[78:79], v[58:59], v[78:79], v[90:91] op_sel:[0,1,0]
	v_pk_fma_f32 v[90:91], v[56:57], v[80:81], v[94:95] op_sel_hi:[1,0,1]
	v_pk_fma_f32 v[78:79], v[54:55], v[80:81], v[78:79] op_sel_hi:[1,0,1]
	v_mov_b32_e32 v80, v81
	v_pk_fma_f32 v[90:91], v[52:53], v[80:81], v[90:91] op_sel_hi:[1,0,1]
	v_pk_fma_f32 v[78:79], v[50:51], v[80:81], v[78:79] op_sel_hi:[1,0,1]
	s_waitcnt lgkmcnt(0)
	v_pk_fma_f32 v[80:81], v[48:49], v[82:83], v[90:91] op_sel_hi:[1,0,1]
	v_pk_fma_f32 v[78:79], v[46:47], v[82:83], v[78:79] op_sel_hi:[1,0,1]
	v_pk_fma_f32 v[80:81], v[44:45], v[82:83], v[80:81] op_sel:[0,1,0]
	v_pk_fma_f32 v[78:79], v[42:43], v[82:83], v[78:79] op_sel:[0,1,0]
	v_pk_fma_f32 v[80:81], v[40:41], v[84:85], v[80:81] op_sel_hi:[1,0,1]
	v_pk_fma_f32 v[78:79], v[38:39], v[84:85], v[78:79] op_sel_hi:[1,0,1]
	v_mov_b32_e32 v82, v85
	v_pk_fma_f32 v[80:81], v[36:37], v[82:83], v[80:81] op_sel_hi:[1,0,1]
	v_pk_fma_f32 v[78:79], v[34:35], v[82:83], v[78:79] op_sel_hi:[1,0,1]
	global_store_dwordx4 v[188:189], v[78:81], off offset:-1536 nt
	ds_read_b128 v[82:85], v161 offset:12288
	ds_read_b128 v[94:97], v161 offset:8192
	ds_read_b128 v[78:81], v161 offset:8208
	ds_read_b128 v[98:101], v161 offset:12304
	v_pk_mul_f32 v[90:91], v[24:25], v[92:93] op_sel_hi:[1,0]
	v_pk_mul_f32 v[102:103], v[22:23], v[92:93] op_sel_hi:[1,0]
	s_waitcnt lgkmcnt(3)
	v_pk_fma_f32 v[90:91], v[64:65], v[82:83], v[90:91] op_sel_hi:[1,0,1]
	v_pk_fma_f32 v[102:103], v[62:63], v[82:83], v[102:103] op_sel_hi:[1,0,1]
	v_pk_fma_f32 v[90:91], v[60:61], v[82:83], v[90:91] op_sel:[0,1,0]
	v_pk_fma_f32 v[82:83], v[58:59], v[82:83], v[102:103] op_sel:[0,1,0]
	v_pk_fma_f32 v[90:91], v[56:57], v[84:85], v[90:91] op_sel_hi:[1,0,1]
	v_pk_fma_f32 v[82:83], v[54:55], v[84:85], v[82:83] op_sel_hi:[1,0,1]
	v_mov_b32_e32 v84, v85
	v_pk_fma_f32 v[90:91], v[52:53], v[84:85], v[90:91] op_sel_hi:[1,0,1]
	v_pk_fma_f32 v[82:83], v[50:51], v[84:85], v[82:83] op_sel_hi:[1,0,1]
	s_waitcnt lgkmcnt(0)
	v_pk_fma_f32 v[84:85], v[48:49], v[98:99], v[90:91] op_sel_hi:[1,0,1]
	v_pk_fma_f32 v[82:83], v[46:47], v[98:99], v[82:83] op_sel_hi:[1,0,1]
	v_pk_fma_f32 v[84:85], v[44:45], v[98:99], v[84:85] op_sel:[0,1,0]
	v_pk_fma_f32 v[82:83], v[42:43], v[98:99], v[82:83] op_sel:[0,1,0]
	v_pk_fma_f32 v[84:85], v[40:41], v[100:101], v[84:85] op_sel_hi:[1,0,1]
	v_pk_fma_f32 v[82:83], v[38:39], v[100:101], v[82:83] op_sel_hi:[1,0,1]
	v_mov_b32_e32 v90, v101
	v_pk_fma_f32 v[84:85], v[36:37], v[90:91], v[84:85] op_sel_hi:[1,0,1]
	v_pk_fma_f32 v[82:83], v[34:35], v[90:91], v[82:83] op_sel_hi:[1,0,1]
	global_store_dwordx4 v[188:189], v[82:85], off offset:-1024 nt
	ds_read_b128 v[98:101], v162 offset:8192
	ds_read_b128 v[82:85], v162 offset:8208
	ds_read_b128 v[102:105], v162 offset:12288
	ds_read_b128 v[106:109], v162 offset:12304
	v_mov_b32_e32 v90, v93
	v_pk_mul_f32 v[92:93], v[20:21], v[90:91] op_sel_hi:[1,0]
	v_pk_mul_f32 v[90:91], v[18:19], v[90:91] op_sel_hi:[1,0]
	s_waitcnt lgkmcnt(1)
; #define GAS __attribute__((address_space(1)))
; #define LAS __attribute__((address_space(3)))
; __device__ __forceinline__ void hgrn_sample_loop(Frame& F) {
;     ...
;         for (int j = 0; j < 8; ++j) { const int k = 8 * kg + j; const f32x4 sv = s0[j]; const f32x4 qa = *(const LAS f32x4*)(QT + k * 8), qb = *(const LAS f32x4*)(QT + k * 8 + 4), ka = *(const LAS f32x4*)(K3T + k * 8), kb = *(const LAS f32x4*)(K3T + k * 8 + 4);
;             f32x4 sn = sv * DEC[k];
;             o[0] += sv * qa.x; o[1] += sv * qa.y; o[2] += sv * qa.z; o[3] += sv * qa.w; o[4] += sv * qb.x; o[5] += sv * qb.y; o[6] += sv * qb.z; o[7] += sv * qb.w;
;             sn += vr[0] * ka.x; sn += vr[1] * ka.y; sn += vr[2] * ka.z; sn += vr[3] * ka.w; sn += vr[4] * kb.x; sn += vr[5] * kb.y; sn += vr[6] * kb.z; sn += vr[7] * kb.w;
;             *(GAS f32x4*)(Sout + (size_t)k * HD + v4) = sn; }
	v_pk_fma_f32 v[92:93], v[64:65], v[102:103], v[92:93] op_sel_hi:[1,0,1]
	v_pk_fma_f32 v[90:91], v[62:63], v[102:103], v[90:91] op_sel_hi:[1,0,1]
	v_pk_fma_f32 v[92:93], v[60:61], v[102:103], v[92:93] op_sel:[0,1,0]
	v_pk_fma_f32 v[90:91], v[58:59], v[102:103], v[90:91] op_sel:[0,1,0]
	v_pk_fma_f32 v[92:93], v[56:57], v[104:105], v[92:93] op_sel_hi:[1,0,1]
	v_pk_fma_f32 v[90:91], v[54:55], v[104:105], v[90:91] op_sel_hi:[1,0,1]
	v_mov_b32_e32 v102, v105
	v_pk_fma_f32 v[92:93], v[52:53], v[102:103], v[92:93] op_sel_hi:[1,0,1]
	v_pk_fma_f32 v[90:91], v[50:51], v[102:103], v[90:91] op_sel_hi:[1,0,1]
	s_waitcnt lgkmcnt(0)
	v_pk_fma_f32 v[92:93], v[48:49], v[106:107], v[92:93] op_sel_hi:[1,0,1]
	v_pk_fma_f32 v[90:91], v[46:47], v[106:107], v[90:91] op_sel_hi:[1,0,1]
	v_pk_fma_f32 v[92:93], v[44:45], v[106:107], v[92:93] op_sel:[0,1,0]
	v_pk_fma_f32 v[90:91], v[42:43], v[106:107], v[90:91] op_sel:[0,1,0]
	v_pk_fma_f32 v[92:93], v[40:41], v[108:109], v[92:93] op_sel_hi:[1,0,1]
	v_pk_fma_f32 v[90:91], v[38:39], v[108:109], v[90:91] op_sel_hi:[1,0,1]
	v_mov_b32_e32 v102, v109
	v_pk_fma_f32 v[92:93], v[36:37], v[102:103], v[92:93] op_sel_hi:[1,0,1]
	v_pk_fma_f32 v[90:91], v[34:35], v[102:103], v[90:91] op_sel_hi:[1,0,1]
	global_store_dwordx4 v[188:189], v[90:93], off offset:-512 nt
	ds_read_b128 v[106:109], v163 offset:12288
	ds_read_b128 v[102:105], v163 offset:8192
	ds_read_b128 v[90:93], v163 offset:8208
	ds_read_b128 v[110:113], v163 offset:12304
	v_pk_mul_f32 v[114:115], v[16:17], v[176:177] op_sel_hi:[1,0]
	v_pk_mul_f32 v[116:117], v[14:15], v[176:177] op_sel_hi:[1,0]
	s_waitcnt lgkmcnt(3)
	v_pk_fma_f32 v[114:115], v[64:65], v[106:107], v[114:115] op_sel_hi:[1,0,1]
	v_pk_fma_f32 v[116:117], v[62:63], v[106:107], v[116:117] op_sel_hi:[1,0,1]
	v_pk_fma_f32 v[114:115], v[60:61], v[106:107], v[114:115] op_sel:[0,1,0]
	v_pk_fma_f32 v[106:107], v[58:59], v[106:107], v[116:117] op_sel:[0,1,0]
	v_pk_fma_f32 v[114:115], v[56:57], v[108:109], v[114:115] op_sel_hi:[1,0,1]
	v_pk_fma_f32 v[106:107], v[54:55], v[108:109], v[106:107] op_sel_hi:[1,0,1]
	v_mov_b32_e32 v108, v109
	v_pk_fma_f32 v[114:115], v[52:53], v[108:109], v[114:115] op_sel_hi:[1,0,1]
	v_pk_fma_f32 v[106:107], v[50:51], v[108:109], v[106:107] op_sel_hi:[1,0,1]
	s_waitcnt lgkmcnt(0)
	v_pk_fma_f32 v[108:109], v[48:49], v[110:111], v[114:115] op_sel_hi:[1,0,1]
	v_pk_fma_f32 v[106:107], v[46:47], v[110:111], v[106:107] op_sel_hi:[1,0,1]
	v_pk_fma_f32 v[108:109], v[44:45], v[110:111], v[108:109] op_sel:[0,1,0]
	v_pk_fma_f32 v[106:107], v[42:43], v[110:111], v[106:107] op_sel:[0,1,0]
	v_pk_fma_f32 v[108:109], v[40:41], v[112:113], v[108:109] op_sel_hi:[1,0,1]
	v_pk_fma_f32 v[106:107], v[38:39], v[112:113], v[106:107] op_sel_hi:[1,0,1]
	v_mov_b32_e32 v110, v113
	v_pk_fma_f32 v[108:109], v[36:37], v[110:111], v[108:109] op_sel_hi:[1,0,1]
	v_pk_fma_f32 v[106:107], v[34:35], v[110:111], v[106:107] op_sel_hi:[1,0,1]
	global_store_dwordx4 v[188:189], v[106:109], off nt
	ds_read_b128 v[114:117], v164 offset:12288
	ds_read_b128 v[110:113], v164 offset:8192
	ds_read_b128 v[106:109], v164 offset:8208
	ds_read_b128 v[118:121], v164 offset:12304
	v_pk_mul_f32 v[122:123], v[12:13], v[176:177] op_sel:[0,1]
	v_pk_mul_f32 v[124:125], v[10:11], v[176:177] op_sel:[0,1]
	s_waitcnt lgkmcnt(3)
	v_pk_fma_f32 v[122:123], v[64:65], v[114:115], v[122:123] op_sel_hi:[1,0,1]
	v_pk_fma_f32 v[124:125], v[62:63], v[114:115], v[124:125] op_sel_hi:[1,0,1]
	v_pk_fma_f32 v[122:123], v[60:61], v[114:115], v[122:123] op_sel:[0,1,0]
	v_pk_fma_f32 v[114:115], v[58:59], v[114:115], v[124:125] op_sel:[0,1,0]
	v_pk_fma_f32 v[122:123], v[56:57], v[116:117], v[122:123] op_sel_hi:[1,0,1]
	v_pk_fma_f32 v[114:115], v[54:55], v[116:117], v[114:115] op_sel_hi:[1,0,1]
	v_mov_b32_e32 v116, v117
	v_pk_fma_f32 v[122:123], v[52:53], v[116:117], v[122:123] op_sel_hi:[1,0,1]
	v_pk_fma_f32 v[114:115], v[50:51], v[116:117], v[114:115] op_sel_hi:[1,0,1]
	s_waitcnt lgkmcnt(0)
	v_pk_fma_f32 v[116:117], v[48:49], v[118:119], v[122:123] op_sel_hi:[1,0,1]
	v_pk_fma_f32 v[114:115], v[46:47], v[118:119], v[114:115] op_sel_hi:[1,0,1]
	v_pk_fma_f32 v[116:117], v[44:45], v[118:119], v[116:117] op_sel:[0,1,0]
	v_pk_fma_f32 v[114:115], v[42:43], v[118:119], v[114:115] op_sel:[0,1,0]
	v_pk_fma_f32 v[116:117], v[40:41], v[120:121], v[116:117] op_sel_hi:[1,0,1]
	v_pk_fma_f32 v[114:115], v[38:39], v[120:121], v[114:115] op_sel_hi:[1,0,1]
	v_mov_b32_e32 v118, v121
	v_pk_fma_f32 v[116:117], v[36:37], v[118:119], v[116:117] op_sel_hi:[1,0,1]
	v_pk_fma_f32 v[114:115], v[34:35], v[118:119], v[114:115] op_sel_hi:[1,0,1]
	global_store_dwordx4 v[188:189], v[114:117], off offset:512 nt
	ds_read_b128 v[122:125], v165 offset:12288
	ds_read_b128 v[118:121], v165 offset:8192
	ds_read_b128 v[114:117], v165 offset:8208
	ds_read_b128 v[126:129], v165 offset:12304
	v_pk_mul_f32 v[176:177], v[8:9], v[178:179] op_sel_hi:[1,0]
	v_pk_mul_f32 v[180:181], v[6:7], v[178:179] op_sel_hi:[1,0]
	s_waitcnt lgkmcnt(3)
; #define GAS __attribute__((address_space(1)))
; #define LAS __attribute__((address_space(3)))
; __device__ __forceinline__ void hgrn_sample_loop(Frame& F) {
;     ...
;         for (int j = 0; j < 8; ++j) { const int k = 8 * kg + j; const f32x4 sv = s0[j]; const f32x4 qa = *(const LAS f32x4*)(QT + k * 8), qb = *(const LAS f32x4*)(QT + k * 8 + 4), ka = *(const LAS f32x4*)(K3T + k * 8), kb = *(const LAS f32x4*)(K3T + k * 8 + 4);
;             f32x4 sn = sv * DEC[k];
;             o[0] += sv * qa.x; o[1] += sv * qa.y; o[2] += sv * qa.z; o[3] += sv * qa.w; o[4] += sv * qb.x; o[5] += sv * qb.y; o[6] += sv * qb.z; o[7] += sv * qb.w;
;             sn += vr[0] * ka.x; sn += vr[1] * ka.y; sn += vr[2] * ka.z; sn += vr[3] * ka.w; sn += vr[4] * kb.x; sn += vr[5] * kb.y; sn += vr[6] * kb.z; sn += vr[7] * kb.w;
;             *(GAS f32x4*)(Sout + (size_t)k * HD + v4) = sn; }
;         if (idx + F.G < SB_B * HH) {
; #pragma unroll
;             for (int j = 0; j < 8; ++j) s0[j] = *(const GAS f32x4*)(F.in[4] + (size_t)(idx + F.G) * HD * HD + (size_t)(8 * kg + j) * HD + v4); }
	v_pk_fma_f32 v[176:177], v[64:65], v[122:123], v[176:177] op_sel_hi:[1,0,1]
	v_pk_fma_f32 v[180:181], v[62:63], v[122:123], v[180:181] op_sel_hi:[1,0,1]
	v_pk_fma_f32 v[176:177], v[60:61], v[122:123], v[176:177] op_sel:[0,1,0]
	v_pk_fma_f32 v[122:123], v[58:59], v[122:123], v[180:181] op_sel:[0,1,0]
	v_pk_fma_f32 v[176:177], v[56:57], v[124:125], v[176:177] op_sel_hi:[1,0,1]
	v_pk_fma_f32 v[122:123], v[54:55], v[124:125], v[122:123] op_sel_hi:[1,0,1]
	v_mov_b32_e32 v124, v125
	v_pk_fma_f32 v[176:177], v[52:53], v[124:125], v[176:177] op_sel_hi:[1,0,1]
	v_pk_fma_f32 v[122:123], v[50:51], v[124:125], v[122:123] op_sel_hi:[1,0,1]
	s_waitcnt lgkmcnt(0)
	v_pk_fma_f32 v[124:125], v[48:49], v[126:127], v[176:177] op_sel_hi:[1,0,1]
	v_pk_fma_f32 v[122:123], v[46:47], v[126:127], v[122:123] op_sel_hi:[1,0,1]
	v_pk_fma_f32 v[124:125], v[44:45], v[126:127], v[124:125] op_sel:[0,1,0]
	v_pk_fma_f32 v[122:123], v[42:43], v[126:127], v[122:123] op_sel:[0,1,0]
	v_pk_fma_f32 v[124:125], v[40:41], v[128:129], v[124:125] op_sel_hi:[1,0,1]
	v_pk_fma_f32 v[122:123], v[38:39], v[128:129], v[122:123] op_sel_hi:[1,0,1]
	v_mov_b32_e32 v126, v129
	v_pk_fma_f32 v[124:125], v[36:37], v[126:127], v[124:125] op_sel_hi:[1,0,1]
	v_pk_fma_f32 v[122:123], v[34:35], v[126:127], v[122:123] op_sel_hi:[1,0,1]
	global_store_dwordx4 v[188:189], v[122:125], off offset:1024 nt
	ds_read_b128 v[126:129], v166 offset:8192
	ds_read_b128 v[122:125], v166 offset:8208
	ds_read_b128 v[180:183], v166 offset:12288
	ds_read_b128 v[184:187], v166 offset:12304
	v_mov_b32_e32 v176, v179
	v_pk_mul_f32 v[178:179], v[4:5], v[176:177] op_sel_hi:[1,0]
	v_pk_mul_f32 v[176:177], v[2:3], v[176:177] op_sel_hi:[1,0]
	s_waitcnt lgkmcnt(1)
	v_pk_fma_f32 v[64:65], v[64:65], v[180:181], v[178:179] op_sel_hi:[1,0,1]
	v_pk_fma_f32 v[62:63], v[62:63], v[180:181], v[176:177] op_sel_hi:[1,0,1]
	v_pk_fma_f32 v[60:61], v[60:61], v[180:181], v[64:65] op_sel:[0,1,0]
	v_pk_fma_f32 v[58:59], v[58:59], v[180:181], v[62:63] op_sel:[0,1,0]
	v_pk_fma_f32 v[56:57], v[56:57], v[182:183], v[60:61] op_sel_hi:[1,0,1]
	v_pk_fma_f32 v[54:55], v[54:55], v[182:183], v[58:59] op_sel_hi:[1,0,1]
	v_mov_b32_e32 v58, v183
	v_pk_fma_f32 v[52:53], v[52:53], v[58:59], v[56:57] op_sel_hi:[1,0,1]
	v_pk_fma_f32 v[50:51], v[50:51], v[58:59], v[54:55] op_sel_hi:[1,0,1]
	s_waitcnt lgkmcnt(0)
	v_pk_fma_f32 v[48:49], v[48:49], v[184:185], v[52:53] op_sel_hi:[1,0,1]
	v_pk_fma_f32 v[46:47], v[46:47], v[184:185], v[50:51] op_sel_hi:[1,0,1]
	v_pk_fma_f32 v[44:45], v[44:45], v[184:185], v[48:49] op_sel:[0,1,0]
	v_pk_fma_f32 v[42:43], v[42:43], v[184:185], v[46:47] op_sel:[0,1,0]
	v_pk_fma_f32 v[40:41], v[40:41], v[186:187], v[44:45] op_sel_hi:[1,0,1]
	v_pk_fma_f32 v[38:39], v[38:39], v[186:187], v[42:43] op_sel_hi:[1,0,1]
	v_mov_b32_e32 v42, v187
	s_add_i32 s34, s52, s34
	v_pk_fma_f32 v[36:37], v[36:37], v[42:43], v[40:41] op_sel_hi:[1,0,1]
	v_pk_fma_f32 v[34:35], v[34:35], v[42:43], v[38:39] op_sel_hi:[1,0,1]
	s_cmpk_gt_i32 s34, 0x1ff
	global_store_dwordx4 v[188:189], v[34:37], off offset:1536 nt
	s_cselect_b64 s[14:15], -1, 0
	v_mov_b64_e32 v[40:41], v[28:29]
	v_mov_b64_e32 v[36:37], v[32:33]
	v_mov_b64_e32 v[44:45], v[24:25]
	v_mov_b64_e32 v[48:49], v[20:21]
	v_mov_b64_e32 v[52:53], v[16:17]
	v_mov_b64_e32 v[56:57], v[12:13]
	v_mov_b64_e32 v[60:61], v[8:9]
	v_mov_b64_e32 v[64:65], v[4:5]
	s_and_b64 vcc, exec, s[14:15]
	v_mov_b64_e32 v[34:35], v[30:31]
	v_mov_b64_e32 v[38:39], v[26:27]
	v_mov_b64_e32 v[42:43], v[22:23]
	v_mov_b64_e32 v[46:47], v[18:19]
	v_mov_b64_e32 v[50:51], v[14:15]
	v_mov_b64_e32 v[54:55], v[10:11]
	v_mov_b64_e32 v[58:59], v[6:7]
	v_mov_b64_e32 v[62:63], v[2:3]
	s_cbranch_vccnz .LBB0_279
	v_lshl_add_u64 v[62:63], v[140:141], 0, v[138:139]
	global_load_dwordx4 v[34:37], v[62:63], off nt
	global_load_dwordx4 v[38:41], v[62:63], off offset:512 nt
	global_load_dwordx4 v[42:45], v[62:63], off offset:1024 nt
	global_load_dwordx4 v[46:49], v[62:63], off offset:1536 nt
	global_load_dwordx4 v[50:53], v[62:63], off offset:2048 nt
	global_load_dwordx4 v[54:57], v[62:63], off offset:2560 nt
	global_load_dwordx4 v[58:61], v[62:63], off offset:3072 nt
	s_nop 0
	global_load_dwordx4 v[62:65], v[62:63], off offset:3584 nt
	s_branch .LBB0_279

; #define GAS __attribute__((address_space(1)))
; #define LAS __attribute__((address_space(3)))
; __device__ __forceinline__ void hgrn_sample_loop(Frame& F) {
;     const int tid = F.tid;
;     LAS float* Qs = (LAS float*)(F.lds + LX_Q); LAS float* K2 = (LAS float*)(F.lds + LX_K2); LAS float* QT = (LAS float*)(F.lds + LX_QT); LAS float* K3T = (LAS float*)(F.lds + LX_K3T); LAS float* Vs = (LAS float*)(F.lds + LX_V);
;     LAS float* DEC = (LAS float*)(F.lds + LX_DEC); LAS float* ATT = (LAS float*)(F.lds + LX_ATT); LAS float* OP = (LAS float*)(F.lds + LX_OP); LAS float* OT = (LAS float*)(F.lds + LX_OT);
;     const bf16* PB = (const bf16*)(F.ws + WS_PB); const float* FZ = (const float*)(F.ws + WS_FZ); bf16* MIX = (bf16*)(F.ws + WS_MIX);
;     const int v4 = (tid & 31) * 4, kg = tid >> 5;
;     int idx = F.bid; if (idx >= SB_B * HH) return;
;     f32x4 s0[8];
; #pragma unroll
;     for (int j = 0; j < 8; ++j) s0[j] = *(const GAS f32x4*)(F.in[4] + (size_t)idx * HD * HD + (size_t)(8 * kg + j) * HD + v4);
.LBB0_449:
	s_cmpk_gt_i32 s2, 0x1ff
	v_readlane_b32 s96, v238, 53
	s_cbranch_scc1 .LBB0_462
	s_ashr_i32 s3, s2, 31
	v_readlane_b32 s60, v238, 4
	v_lshrrev_b32_e32 v36, 5, v0
	s_lshl_b64 s[12:13], s[2:3], 16
	v_readlane_b32 s68, v238, 12
	v_lshlrev_b32_e32 v4, 3, v36
	v_mov_b32_e32 v133, 0
	v_readlane_b32 s69, v238, 13
	s_add_u32 s0, s68, s12
	v_lshlrev_b32_e32 v6, 4, v0
	v_or_b32_e32 v37, 1, v4
	v_or_b32_e32 v38, 2, v4
	v_or_b32_e32 v39, 3, v4
	v_or_b32_e32 v40, 4, v4
	v_or_b32_e32 v41, 5, v4
	v_or_b32_e32 v42, 6, v4
	v_or_b32_e32 v43, 7, v4
	s_addc_u32 s1, s69, s13
	v_and_b32_e32 v34, 0x1f0, v6
	v_mov_b32_e32 v35, v133
	v_lshlrev_b32_e32 v130, 12, v36
	v_mov_b32_e32 v131, v133
	v_lshlrev_b32_e32 v132, 9, v37
	v_lshlrev_b32_e32 v18, 9, v38
	v_mov_b32_e32 v19, v133
	v_lshlrev_b32_e32 v20, 9, v39
	v_mov_b32_e32 v21, v133
	v_lshlrev_b32_e32 v10, 9, v40
	v_mov_b32_e32 v11, v133
	v_lshlrev_b32_e32 v12, 9, v41
	v_mov_b32_e32 v13, v133
	v_lshlrev_b32_e32 v2, 9, v42
	v_mov_b32_e32 v3, v133
	v_lshlrev_b32_e32 v4, 9, v43
	v_mov_b32_e32 v5, v133
	v_lshl_add_u64 v[26:27], s[0:1], 0, v[34:35]
	v_lshl_add_u64 v[4:5], v[26:27], 0, v[4:5]
	v_lshl_add_u64 v[6:7], v[26:27], 0, v[2:3]
	v_lshl_add_u64 v[12:13], v[26:27], 0, v[12:13]
	v_lshl_add_u64 v[14:15], v[26:27], 0, v[10:11]
	v_lshl_add_u64 v[20:21], v[26:27], 0, v[20:21]
	v_lshl_add_u64 v[22:23], v[26:27], 0, v[18:19]
	v_lshl_add_u64 v[28:29], v[26:27], 0, v[132:133]
	v_lshl_add_u64 v[30:31], v[26:27], 0, v[130:131]
	global_load_dwordx4 v[2:5], v[4:5], off nt
	s_nop 0
	global_load_dwordx4 v[6:9], v[6:7], off nt
	s_nop 0
	global_load_dwordx4 v[10:13], v[12:13], off nt
	s_nop 0
	global_load_dwordx4 v[14:17], v[14:15], off nt
	s_nop 0
	global_load_dwordx4 v[18:21], v[20:21], off nt
	s_nop 0
	global_load_dwordx4 v[22:25], v[22:23], off nt
	s_nop 0
	global_load_dwordx4 v[26:29], v[28:29], off nt
	s_nop 0
	global_load_dwordx4 v[30:33], v[30:31], off nt
	v_and_b32_e32 v44, 7, v0
	v_lshrrev_b32_e32 v45, 6, v0
	v_bfe_u32 v46, v0, 3, 3
	v_lshlrev_b32_e32 v47, 9, v45
	v_lshlrev_b32_e32 v48, 2, v44
	v_add3_u32 v147, 0, v47, v48
	v_lshlrev_b32_e32 v47, 9, v46
	v_add3_u32 v148, 0, v47, v48
	v_mbcnt_lo_u32_b32 v47, -1, 0
	v_mbcnt_hi_u32_b32 v47, -1, v47
	s_movk_i32 s0, 0x80
	v_and_b32_e32 v49, 64, v47
	v_subrev_co_u32_e32 v132, vcc, s0, v0
	v_xor_b32_e32 v48, 1, v47
	v_add_u32_e32 v49, 64, v49
	s_xor_b64 s[4:5], vcc, -1
	v_cmp_lt_i32_e32 vcc, v48, v49
	v_add_u32_e32 v144, 0, v34
	v_lshrrev_b32_e32 v34, 3, v0
	v_cndmask_b32_e32 v48, v47, v48, vcc
	v_lshlrev_b32_e32 v149, 2, v48
	v_xor_b32_e32 v48, 2, v47
	v_cmp_lt_i32_e32 vcc, v48, v49
	v_lshl_add_u32 v152, v34, 2, 0
	v_xor_b32_e32 v34, 8, v47
	v_cndmask_b32_e32 v48, v47, v48, vcc
	v_lshlrev_b32_e32 v150, 2, v48
	v_xor_b32_e32 v48, 4, v47
	v_cmp_lt_i32_e32 vcc, v48, v49
	v_cmp_eq_u32_e64 s[6:7], 0, v44
	v_lshl_add_u32 v153, v92, 2, 0
	v_cndmask_b32_e32 v48, v47, v48, vcc
	v_cmp_lt_i32_e32 vcc, v34, v49
	v_lshl_add_u32 v158, v36, 8, 0
	v_mul_i32_i24_e32 v44, 0xffffff20, v36
	v_and_b32_e32 v36, 0x180, v0
	v_cndmask_b32_e32 v34, v47, v34, vcc
	v_lshl_add_u32 v166, v36, 2, v153
	v_lshrrev_b32_e32 v36, 2, v0
	v_lshlrev_b32_e32 v155, 2, v34
	v_xor_b32_e32 v34, 16, v47
	v_lshl_add_u32 v160, v38, 5, 0
	v_and_b32_e32 v38, 0x60, v36
	s_movk_i32 s3, 0x380
	v_mov_b32_e32 v36, 0x200
	s_add_i32 s10, s2, s52
	v_cmp_lt_i32_e32 vcc, v34, v49
	v_bitop3_b32 v36, v0, s3, v36 bitop3:0xc8
	s_lshl_b32 s3, s96, 9
	s_ashr_i32 s11, s10, 31
	v_cndmask_b32_e32 v34, v47, v34, vcc
	s_add_i32 s3, s3, 0
	s_lshl_b64 s[10:11], s[10:11], 16
	v_lshlrev_b32_e32 v156, 2, v34
	v_xor_b32_e32 v34, 32, v47
	v_readlane_b32 s16, v238, 29
	s_add_u32 s10, s68, s10
	v_cmp_lt_i32_e32 vcc, v34, v49
	v_lshl_add_u32 v168, v36, 2, v153
	v_lshlrev_b32_e32 v36, 3, v154
	v_readlane_b32 s22, v238, 35
	s_addc_u32 s11, s69, s11
	v_cndmask_b32_e32 v34, v47, v34, vcc
	v_add_u32_e32 v170, s3, v36
	v_lshl_add_u64 v[138:139], s[10:11], 0, v[130:131]
	s_lshl_b64 s[10:11], s[52:53], 16
	s_lshl_b32 s3, s2, 1
	s_lshl_b32 s22, s52, 1
	v_lshlrev_b32_e32 v157, 2, v34
	v_or_b32_e32 v34, 0x200, v0
	v_lshl_add_u32 v159, v37, 5, 0
	v_mov_b32_e32 v37, v133
	v_readlane_b32 s18, v238, 31
	v_readlane_b32 s19, v238, 32
	s_add_u32 s12, s48, s12
	v_lshl_add_u32 v145, v0, 2, 0
	v_lshrrev_b32_e32 v34, 2, v34
	v_lshl_add_u64 v[134:135], s[18:19], 0, v[36:37]
	v_and_b32_e32 v36, 31, v0
	s_addc_u32 s13, s49, s13
	s_movk_i32 s0, 0x100
	v_mad_u32_u24 v146, v0, 28, v145
	v_mul_i32_i24_e32 v35, 0xffffffe4, v0
	v_lshl_add_u32 v161, v39, 5, 0
	v_and_b32_e32 v39, 0xe0, v34
	v_lshlrev_b32_e32 v34, 1, v154
	v_readlane_b32 s23, v238, 36
	v_lshlrev_b32_e32 v136, 4, v36
	v_lshl_add_u64 v[36:37], s[12:13], 0, v[130:131]
	s_mov_b64 s[12:13], 0x4820800
	v_cmp_gt_u32_e64 s[0:1], s0, v0
	v_lshlrev_b32_e32 v151, 2, v48
	v_cmp_gt_u32_e64 s[8:9], v46, v45
	v_lshl_add_u32 v162, v40, 5, 0
	v_lshl_add_u32 v163, v41, 5, 0
	v_lshl_add_u32 v164, v42, 5, 0
	v_lshl_add_u32 v165, v43, 5, 0
	v_add_u32_e32 v167, 0x6300, v166
	v_add_u32_e32 v169, 0x6300, v168
	v_mov_b32_e32 v137, v133
	v_lshl_add_u64 v[140:141], v[36:37], 0, s[12:13]
	v_lshlrev_b64 v[142:143], 1, v[132:133]
	v_add_u32_e32 v131, v146, v35
	v_add_u32_e32 v171, v158, v44
	v_add_u32_e32 v172, 0, v38
	v_add_u32_e32 v173, 0, v39
	v_lshlrev_b32_e32 v132, 1, v34
	v_mov_b32_e32 v174, 0x358637bd
	s_mov_b32 s23, s2
	v_readlane_b32 s61, v238, 5
	v_readlane_b32 s62, v238, 6
	v_readlane_b32 s63, v238, 7
	v_readlane_b32 s64, v238, 8
	v_readlane_b32 s65, v238, 9
	v_readlane_b32 s66, v238, 10
	v_readlane_b32 s67, v238, 11
	v_readlane_b32 s70, v238, 14
	v_readlane_b32 s71, v238, 15
	v_readlane_b32 s72, v238, 16
	v_readlane_b32 s73, v238, 17
	v_readlane_b32 s74, v238, 18
	v_readlane_b32 s75, v238, 19
	v_readlane_b32 s17, v238, 30
	v_readlane_b32 s20, v238, 33
	v_readlane_b32 s21, v238, 34
	v_readlane_b32 s24, v238, 37
	v_readlane_b32 s25, v238, 38
	v_readlane_b32 s26, v238, 39
	v_readlane_b32 s27, v238, 40
	v_readlane_b32 s28, v238, 41
	v_readlane_b32 s29, v238, 42
	v_readlane_b32 s30, v238, 43
	v_readlane_b32 s31, v238, 44
	s_branch .LBB0_452

; #define GAS __attribute__((address_space(1)))
; #define LAS __attribute__((address_space(3)))
; __device__ __forceinline__ void hgrn_sample_loop(Frame& F) {
;     ...
;         f32x4 vr[8], o[8];
; #pragma unroll
;         for (int t = 0; t < 8; ++t) { vr[t] = *(const LAS f32x4*)(Vs + t * 128 + v4); o[t] = (f32x4){0.f, 0.f, 0.f, 0.f}; }
; #pragma unroll
;         for (int j = 0; j < 8; ++j) { const int k = 8 * kg + j; const f32x4 sv = s0[j]; const f32x4 qa = *(const LAS f32x4*)(QT + k * 8), qb = *(const LAS f32x4*)(QT + k * 8 + 4), ka = *(const LAS f32x4*)(K3T + k * 8), kb = *(const LAS f32x4*)(K3T + k * 8 + 4);
;             f32x4 sn = sv * DEC[k];
;             o[0] += sv * qa.x; o[1] += sv * qa.y; o[2] += sv * qa.z; o[3] += sv * qa.w; o[4] += sv * qb.x; o[5] += sv * qb.y; o[6] += sv * qb.z; o[7] += sv * qb.w;
;             sn += vr[0] * ka.x; sn += vr[1] * ka.y; sn += vr[2] * ka.z; sn += vr[3] * ka.w; sn += vr[4] * kb.x; sn += vr[5] * kb.y; sn += vr[6] * kb.z; sn += vr[7] * kb.w;
;             *(GAS f32x4*)(Sout + (size_t)k * HD + v4) = sn; }
.LBB0_460:
	s_or_b64 exec, exec, s[14:15]
	ds_read_b128 v[62:65], v144 offset:16384
	ds_read_b128 v[58:61], v144 offset:16896
	ds_read_b128 v[54:57], v144 offset:17408
	ds_read_b128 v[50:53], v144 offset:17920
	ds_read_b128 v[46:49], v144 offset:18432
	ds_read_b128 v[42:45], v144 offset:18944
	ds_read_b128 v[38:41], v144 offset:19456
	s_waitcnt lgkmcnt(7)
	ds_read_b128 v[34:37], v144 offset:19968
	ds_read_b128 v[90:93], v171 offset:20480
	ds_read_b128 v[70:73], v158 offset:8192
	ds_read_b128 v[66:69], v158 offset:8208
	ds_read_b128 v[74:77], v158 offset:12288
	ds_read_b128 v[78:81], v158 offset:12304
	ds_read_b128 v[176:179], v171 offset:20496
	s_waitcnt vmcnt(0) lgkmcnt(5)
	v_pk_mul_f32 v[82:83], v[32:33], v[90:91] op_sel_hi:[1,0]
	v_pk_mul_f32 v[84:85], v[30:31], v[90:91] op_sel_hi:[1,0]
	s_waitcnt lgkmcnt(2)
	v_pk_fma_f32 v[82:83], v[64:65], v[74:75], v[82:83] op_sel_hi:[1,0,1]
	v_pk_fma_f32 v[84:85], v[62:63], v[74:75], v[84:85] op_sel_hi:[1,0,1]
	v_pk_fma_f32 v[82:83], v[60:61], v[74:75], v[82:83] op_sel:[0,1,0]
	v_pk_fma_f32 v[74:75], v[58:59], v[74:75], v[84:85] op_sel:[0,1,0]
	v_pk_fma_f32 v[82:83], v[56:57], v[76:77], v[82:83] op_sel_hi:[1,0,1]
	v_pk_fma_f32 v[74:75], v[54:55], v[76:77], v[74:75] op_sel_hi:[1,0,1]
	v_mov_b32_e32 v76, v77
	v_pk_fma_f32 v[82:83], v[52:53], v[76:77], v[82:83] op_sel_hi:[1,0,1]
	v_pk_fma_f32 v[74:75], v[50:51], v[76:77], v[74:75] op_sel_hi:[1,0,1]
	s_waitcnt lgkmcnt(1)
	v_pk_fma_f32 v[76:77], v[48:49], v[78:79], v[82:83] op_sel_hi:[1,0,1]
	v_pk_fma_f32 v[74:75], v[46:47], v[78:79], v[74:75] op_sel_hi:[1,0,1]
	v_pk_fma_f32 v[76:77], v[44:45], v[78:79], v[76:77] op_sel:[0,1,0]
	v_pk_fma_f32 v[74:75], v[42:43], v[78:79], v[74:75] op_sel:[0,1,0]
	v_pk_fma_f32 v[76:77], v[40:41], v[80:81], v[76:77] op_sel_hi:[1,0,1]
	v_pk_fma_f32 v[74:75], v[38:39], v[80:81], v[74:75] op_sel_hi:[1,0,1]
	v_mov_b32_e32 v78, v81
	v_pk_fma_f32 v[76:77], v[36:37], v[78:79], v[76:77] op_sel_hi:[1,0,1]
	v_pk_fma_f32 v[74:75], v[34:35], v[78:79], v[74:75] op_sel_hi:[1,0,1]
	v_lshl_add_u64 v[188:189], v[140:141], 0, v[136:137]
	global_store_dwordx4 v[188:189], v[74:77], off offset:-2048 nt
	ds_read_b128 v[78:81], v159 offset:12288
	ds_read_b128 v[86:89], v159 offset:8192
	ds_read_b128 v[74:77], v159 offset:8208
	ds_read_b128 v[82:85], v159 offset:12304
	v_pk_mul_f32 v[94:95], v[28:29], v[90:91] op_sel:[0,1]
	v_pk_mul_f32 v[90:91], v[26:27], v[90:91] op_sel:[0,1]
	s_waitcnt lgkmcnt(3)
	v_pk_fma_f32 v[94:95], v[64:65], v[78:79], v[94:95] op_sel_hi:[1,0,1]
	v_pk_fma_f32 v[90:91], v[62:63], v[78:79], v[90:91] op_sel_hi:[1,0,1]
	v_pk_fma_f32 v[94:95], v[60:61], v[78:79], v[94:95] op_sel:[0,1,0]
	v_pk_fma_f32 v[78:79], v[58:59], v[78:79], v[90:91] op_sel:[0,1,0]
	v_pk_fma_f32 v[90:91], v[56:57], v[80:81], v[94:95] op_sel_hi:[1,0,1]
	v_pk_fma_f32 v[78:79], v[54:55], v[80:81], v[78:79] op_sel_hi:[1,0,1]
	v_mov_b32_e32 v80, v81
	v_pk_fma_f32 v[90:91], v[52:53], v[80:81], v[90:91] op_sel_hi:[1,0,1]
	v_pk_fma_f32 v[78:79], v[50:51], v[80:81], v[78:79] op_sel_hi:[1,0,1]
	s_waitcnt lgkmcnt(0)
	v_pk_fma_f32 v[80:81], v[48:49], v[82:83], v[90:91] op_sel_hi:[1,0,1]
	v_pk_fma_f32 v[78:79], v[46:47], v[82:83], v[78:79] op_sel_hi:[1,0,1]
	v_pk_fma_f32 v[80:81], v[44:45], v[82:83], v[80:81] op_sel:[0,1,0]
	v_pk_fma_f32 v[78:79], v[42:43], v[82:83], v[78:79] op_sel:[0,1,0]
	v_pk_fma_f32 v[80:81], v[40:41], v[84:85], v[80:81] op_sel_hi:[1,0,1]
	v_pk_fma_f32 v[78:79], v[38:39], v[84:85], v[78:79] op_sel_hi:[1,0,1]
	v_mov_b32_e32 v82, v85
	v_pk_fma_f32 v[80:81], v[36:37], v[82:83], v[80:81] op_sel_hi:[1,0,1]
	v_pk_fma_f32 v[78:79], v[34:35], v[82:83], v[78:79] op_sel_hi:[1,0,1]
	global_store_dwordx4 v[188:189], v[78:81], off offset:-1536 nt
	ds_read_b128 v[82:85], v160 offset:12288
	ds_read_b128 v[94:97], v160 offset:8192
	ds_read_b128 v[78:81], v160 offset:8208
	ds_read_b128 v[98:101], v160 offset:12304
	v_pk_mul_f32 v[90:91], v[24:25], v[92:93] op_sel_hi:[1,0]
	v_pk_mul_f32 v[102:103], v[22:23], v[92:93] op_sel_hi:[1,0]
	s_waitcnt lgkmcnt(3)
	v_pk_fma_f32 v[90:91], v[64:65], v[82:83], v[90:91] op_sel_hi:[1,0,1]
	v_pk_fma_f32 v[102:103], v[62:63], v[82:83], v[102:103] op_sel_hi:[1,0,1]
	v_pk_fma_f32 v[90:91], v[60:61], v[82:83], v[90:91] op_sel:[0,1,0]
	v_pk_fma_f32 v[82:83], v[58:59], v[82:83], v[102:103] op_sel:[0,1,0]
	v_pk_fma_f32 v[90:91], v[56:57], v[84:85], v[90:91] op_sel_hi:[1,0,1]
	v_pk_fma_f32 v[82:83], v[54:55], v[84:85], v[82:83] op_sel_hi:[1,0,1]
	v_mov_b32_e32 v84, v85
	v_pk_fma_f32 v[90:91], v[52:53], v[84:85], v[90:91] op_sel_hi:[1,0,1]
	v_pk_fma_f32 v[82:83], v[50:51], v[84:85], v[82:83] op_sel_hi:[1,0,1]
	s_waitcnt lgkmcnt(0)
	v_pk_fma_f32 v[84:85], v[48:49], v[98:99], v[90:91] op_sel_hi:[1,0,1]
	v_pk_fma_f32 v[82:83], v[46:47], v[98:99], v[82:83] op_sel_hi:[1,0,1]
	v_pk_fma_f32 v[84:85], v[44:45], v[98:99], v[84:85] op_sel:[0,1,0]
	v_pk_fma_f32 v[82:83], v[42:43], v[98:99], v[82:83] op_sel:[0,1,0]
	v_pk_fma_f32 v[84:85], v[40:41], v[100:101], v[84:85] op_sel_hi:[1,0,1]
	v_pk_fma_f32 v[82:83], v[38:39], v[100:101], v[82:83] op_sel_hi:[1,0,1]
	v_mov_b32_e32 v90, v101
	v_pk_fma_f32 v[84:85], v[36:37], v[90:91], v[84:85] op_sel_hi:[1,0,1]
	v_pk_fma_f32 v[82:83], v[34:35], v[90:91], v[82:83] op_sel_hi:[1,0,1]
	global_store_dwordx4 v[188:189], v[82:85], off offset:-1024 nt
	ds_read_b128 v[98:101], v161 offset:8192
	ds_read_b128 v[82:85], v161 offset:8208
	ds_read_b128 v[102:105], v161 offset:12288
	ds_read_b128 v[106:109], v161 offset:12304
	v_mov_b32_e32 v90, v93
	v_pk_mul_f32 v[92:93], v[20:21], v[90:91] op_sel_hi:[1,0]
	v_pk_mul_f32 v[90:91], v[18:19], v[90:91] op_sel_hi:[1,0]
	s_waitcnt lgkmcnt(1)
; #define GAS __attribute__((address_space(1)))
; #define LAS __attribute__((address_space(3)))
; __device__ __forceinline__ void hgrn_sample_loop(Frame& F) {
;     ...
;         for (int j = 0; j < 8; ++j) { const int k = 8 * kg + j; const f32x4 sv = s0[j]; const f32x4 qa = *(const LAS f32x4*)(QT + k * 8), qb = *(const LAS f32x4*)(QT + k * 8 + 4), ka = *(const LAS f32x4*)(K3T + k * 8), kb = *(const LAS f32x4*)(K3T + k * 8 + 4);
;             f32x4 sn = sv * DEC[k];
;             o[0] += sv * qa.x; o[1] += sv * qa.y; o[2] += sv * qa.z; o[3] += sv * qa.w; o[4] += sv * qb.x; o[5] += sv * qb.y; o[6] += sv * qb.z; o[7] += sv * qb.w;
;             sn += vr[0] * ka.x; sn += vr[1] * ka.y; sn += vr[2] * ka.z; sn += vr[3] * ka.w; sn += vr[4] * kb.x; sn += vr[5] * kb.y; sn += vr[6] * kb.z; sn += vr[7] * kb.w;
;             *(GAS f32x4*)(Sout + (size_t)k * HD + v4) = sn; }
	v_pk_fma_f32 v[92:93], v[64:65], v[102:103], v[92:93] op_sel_hi:[1,0,1]
	v_pk_fma_f32 v[90:91], v[62:63], v[102:103], v[90:91] op_sel_hi:[1,0,1]
	v_pk_fma_f32 v[92:93], v[60:61], v[102:103], v[92:93] op_sel:[0,1,0]
	v_pk_fma_f32 v[90:91], v[58:59], v[102:103], v[90:91] op_sel:[0,1,0]
	v_pk_fma_f32 v[92:93], v[56:57], v[104:105], v[92:93] op_sel_hi:[1,0,1]
	v_pk_fma_f32 v[90:91], v[54:55], v[104:105], v[90:91] op_sel_hi:[1,0,1]
	v_mov_b32_e32 v102, v105
	v_pk_fma_f32 v[92:93], v[52:53], v[102:103], v[92:93] op_sel_hi:[1,0,1]
	v_pk_fma_f32 v[90:91], v[50:51], v[102:103], v[90:91] op_sel_hi:[1,0,1]
	s_waitcnt lgkmcnt(0)
	v_pk_fma_f32 v[92:93], v[48:49], v[106:107], v[92:93] op_sel_hi:[1,0,1]
	v_pk_fma_f32 v[90:91], v[46:47], v[106:107], v[90:91] op_sel_hi:[1,0,1]
	v_pk_fma_f32 v[92:93], v[44:45], v[106:107], v[92:93] op_sel:[0,1,0]
	v_pk_fma_f32 v[90:91], v[42:43], v[106:107], v[90:91] op_sel:[0,1,0]
	v_pk_fma_f32 v[92:93], v[40:41], v[108:109], v[92:93] op_sel_hi:[1,0,1]
	v_pk_fma_f32 v[90:91], v[38:39], v[108:109], v[90:91] op_sel_hi:[1,0,1]
	v_mov_b32_e32 v102, v109
	v_pk_fma_f32 v[92:93], v[36:37], v[102:103], v[92:93] op_sel_hi:[1,0,1]
	v_pk_fma_f32 v[90:91], v[34:35], v[102:103], v[90:91] op_sel_hi:[1,0,1]
	global_store_dwordx4 v[188:189], v[90:93], off offset:-512 nt
	ds_read_b128 v[106:109], v162 offset:12288
	ds_read_b128 v[102:105], v162 offset:8192
	ds_read_b128 v[90:93], v162 offset:8208
	ds_read_b128 v[110:113], v162 offset:12304
	v_pk_mul_f32 v[114:115], v[16:17], v[176:177] op_sel_hi:[1,0]
	v_pk_mul_f32 v[116:117], v[14:15], v[176:177] op_sel_hi:[1,0]
	s_waitcnt lgkmcnt(3)
	v_pk_fma_f32 v[114:115], v[64:65], v[106:107], v[114:115] op_sel_hi:[1,0,1]
	v_pk_fma_f32 v[116:117], v[62:63], v[106:107], v[116:117] op_sel_hi:[1,0,1]
	v_pk_fma_f32 v[114:115], v[60:61], v[106:107], v[114:115] op_sel:[0,1,0]
	v_pk_fma_f32 v[106:107], v[58:59], v[106:107], v[116:117] op_sel:[0,1,0]
	v_pk_fma_f32 v[114:115], v[56:57], v[108:109], v[114:115] op_sel_hi:[1,0,1]
	v_pk_fma_f32 v[106:107], v[54:55], v[108:109], v[106:107] op_sel_hi:[1,0,1]
	v_mov_b32_e32 v108, v109
	v_pk_fma_f32 v[114:115], v[52:53], v[108:109], v[114:115] op_sel_hi:[1,0,1]
	v_pk_fma_f32 v[106:107], v[50:51], v[108:109], v[106:107] op_sel_hi:[1,0,1]
	s_waitcnt lgkmcnt(0)
	v_pk_fma_f32 v[108:109], v[48:49], v[110:111], v[114:115] op_sel_hi:[1,0,1]
	v_pk_fma_f32 v[106:107], v[46:47], v[110:111], v[106:107] op_sel_hi:[1,0,1]
	v_pk_fma_f32 v[108:109], v[44:45], v[110:111], v[108:109] op_sel:[0,1,0]
	v_pk_fma_f32 v[106:107], v[42:43], v[110:111], v[106:107] op_sel:[0,1,0]
	v_pk_fma_f32 v[108:109], v[40:41], v[112:113], v[108:109] op_sel_hi:[1,0,1]
	v_pk_fma_f32 v[106:107], v[38:39], v[112:113], v[106:107] op_sel_hi:[1,0,1]
	v_mov_b32_e32 v110, v113
	v_pk_fma_f32 v[108:109], v[36:37], v[110:111], v[108:109] op_sel_hi:[1,0,1]
	v_pk_fma_f32 v[106:107], v[34:35], v[110:111], v[106:107] op_sel_hi:[1,0,1]
	global_store_dwordx4 v[188:189], v[106:109], off nt
	ds_read_b128 v[114:117], v163 offset:12288
	ds_read_b128 v[110:113], v163 offset:8192
	ds_read_b128 v[106:109], v163 offset:8208
	ds_read_b128 v[118:121], v163 offset:12304
	v_pk_mul_f32 v[122:123], v[12:13], v[176:177] op_sel:[0,1]
	v_pk_mul_f32 v[124:125], v[10:11], v[176:177] op_sel:[0,1]
	s_waitcnt lgkmcnt(3)
	v_pk_fma_f32 v[122:123], v[64:65], v[114:115], v[122:123] op_sel_hi:[1,0,1]
	v_pk_fma_f32 v[124:125], v[62:63], v[114:115], v[124:125] op_sel_hi:[1,0,1]
	v_pk_fma_f32 v[122:123], v[60:61], v[114:115], v[122:123] op_sel:[0,1,0]
	v_pk_fma_f32 v[114:115], v[58:59], v[114:115], v[124:125] op_sel:[0,1,0]
	v_pk_fma_f32 v[122:123], v[56:57], v[116:117], v[122:123] op_sel_hi:[1,0,1]
	v_pk_fma_f32 v[114:115], v[54:55], v[116:117], v[114:115] op_sel_hi:[1,0,1]
	v_mov_b32_e32 v116, v117
	v_pk_fma_f32 v[122:123], v[52:53], v[116:117], v[122:123] op_sel_hi:[1,0,1]
	v_pk_fma_f32 v[114:115], v[50:51], v[116:117], v[114:115] op_sel_hi:[1,0,1]
	s_waitcnt lgkmcnt(0)
	v_pk_fma_f32 v[116:117], v[48:49], v[118:119], v[122:123] op_sel_hi:[1,0,1]
	v_pk_fma_f32 v[114:115], v[46:47], v[118:119], v[114:115] op_sel_hi:[1,0,1]
	v_pk_fma_f32 v[116:117], v[44:45], v[118:119], v[116:117] op_sel:[0,1,0]
	v_pk_fma_f32 v[114:115], v[42:43], v[118:119], v[114:115] op_sel:[0,1,0]
	v_pk_fma_f32 v[116:117], v[40:41], v[120:121], v[116:117] op_sel_hi:[1,0,1]
	v_pk_fma_f32 v[114:115], v[38:39], v[120:121], v[114:115] op_sel_hi:[1,0,1]
	v_mov_b32_e32 v118, v121
	v_pk_fma_f32 v[116:117], v[36:37], v[118:119], v[116:117] op_sel_hi:[1,0,1]
	v_pk_fma_f32 v[114:115], v[34:35], v[118:119], v[114:115] op_sel_hi:[1,0,1]
	global_store_dwordx4 v[188:189], v[114:117], off offset:512 nt
	ds_read_b128 v[122:125], v164 offset:12288
	ds_read_b128 v[118:121], v164 offset:8192
	ds_read_b128 v[114:117], v164 offset:8208
	ds_read_b128 v[126:129], v164 offset:12304
	v_pk_mul_f32 v[176:177], v[8:9], v[178:179] op_sel_hi:[1,0]
	v_pk_mul_f32 v[180:181], v[6:7], v[178:179] op_sel_hi:[1,0]
	s_waitcnt lgkmcnt(3)
; #define GAS __attribute__((address_space(1)))
; #define LAS __attribute__((address_space(3)))
; __device__ __forceinline__ void hgrn_sample_loop(Frame& F) {
;     ...
;         for (int j = 0; j < 8; ++j) { const int k = 8 * kg + j; const f32x4 sv = s0[j]; const f32x4 qa = *(const LAS f32x4*)(QT + k * 8), qb = *(const LAS f32x4*)(QT + k * 8 + 4), ka = *(const LAS f32x4*)(K3T + k * 8), kb = *(const LAS f32x4*)(K3T + k * 8 + 4);
;             f32x4 sn = sv * DEC[k];
;             o[0] += sv * qa.x; o[1] += sv * qa.y; o[2] += sv * qa.z; o[3] += sv * qa.w; o[4] += sv * qb.x; o[5] += sv * qb.y; o[6] += sv * qb.z; o[7] += sv * qb.w;
;             sn += vr[0] * ka.x; sn += vr[1] * ka.y; sn += vr[2] * ka.z; sn += vr[3] * ka.w; sn += vr[4] * kb.x; sn += vr[5] * kb.y; sn += vr[6] * kb.z; sn += vr[7] * kb.w;
;             *(GAS f32x4*)(Sout + (size_t)k * HD + v4) = sn; }
;         if (idx + F.G < SB_B * HH) {
; #pragma unroll
;             for (int j = 0; j < 8; ++j) s0[j] = *(const GAS f32x4*)(F.in[4] + (size_t)(idx + F.G) * HD * HD + (size_t)(8 * kg + j) * HD + v4); }
	v_pk_fma_f32 v[176:177], v[64:65], v[122:123], v[176:177] op_sel_hi:[1,0,1]
	v_pk_fma_f32 v[180:181], v[62:63], v[122:123], v[180:181] op_sel_hi:[1,0,1]
	v_pk_fma_f32 v[176:177], v[60:61], v[122:123], v[176:177] op_sel:[0,1,0]
	v_pk_fma_f32 v[122:123], v[58:59], v[122:123], v[180:181] op_sel:[0,1,0]
	v_pk_fma_f32 v[176:177], v[56:57], v[124:125], v[176:177] op_sel_hi:[1,0,1]
	v_pk_fma_f32 v[122:123], v[54:55], v[124:125], v[122:123] op_sel_hi:[1,0,1]
	v_mov_b32_e32 v124, v125
	v_pk_fma_f32 v[176:177], v[52:53], v[124:125], v[176:177] op_sel_hi:[1,0,1]
	v_pk_fma_f32 v[122:123], v[50:51], v[124:125], v[122:123] op_sel_hi:[1,0,1]
	s_waitcnt lgkmcnt(0)
	v_pk_fma_f32 v[124:125], v[48:49], v[126:127], v[176:177] op_sel_hi:[1,0,1]
	v_pk_fma_f32 v[122:123], v[46:47], v[126:127], v[122:123] op_sel_hi:[1,0,1]
	v_pk_fma_f32 v[124:125], v[44:45], v[126:127], v[124:125] op_sel:[0,1,0]
	v_pk_fma_f32 v[122:123], v[42:43], v[126:127], v[122:123] op_sel:[0,1,0]
	v_pk_fma_f32 v[124:125], v[40:41], v[128:129], v[124:125] op_sel_hi:[1,0,1]
	v_pk_fma_f32 v[122:123], v[38:39], v[128:129], v[122:123] op_sel_hi:[1,0,1]
	v_mov_b32_e32 v126, v129
	v_pk_fma_f32 v[124:125], v[36:37], v[126:127], v[124:125] op_sel_hi:[1,0,1]
	v_pk_fma_f32 v[122:123], v[34:35], v[126:127], v[122:123] op_sel_hi:[1,0,1]
	global_store_dwordx4 v[188:189], v[122:125], off offset:1024 nt
	ds_read_b128 v[126:129], v165 offset:8192
	ds_read_b128 v[122:125], v165 offset:8208
	ds_read_b128 v[180:183], v165 offset:12288
	ds_read_b128 v[184:187], v165 offset:12304
	v_mov_b32_e32 v176, v179
	v_pk_mul_f32 v[178:179], v[4:5], v[176:177] op_sel_hi:[1,0]
	v_pk_mul_f32 v[176:177], v[2:3], v[176:177] op_sel_hi:[1,0]
	s_waitcnt lgkmcnt(1)
	v_pk_fma_f32 v[64:65], v[64:65], v[180:181], v[178:179] op_sel_hi:[1,0,1]
	v_pk_fma_f32 v[62:63], v[62:63], v[180:181], v[176:177] op_sel_hi:[1,0,1]
	v_pk_fma_f32 v[60:61], v[60:61], v[180:181], v[64:65] op_sel:[0,1,0]
	v_pk_fma_f32 v[58:59], v[58:59], v[180:181], v[62:63] op_sel:[0,1,0]
	v_pk_fma_f32 v[56:57], v[56:57], v[182:183], v[60:61] op_sel_hi:[1,0,1]
	v_pk_fma_f32 v[54:55], v[54:55], v[182:183], v[58:59] op_sel_hi:[1,0,1]
	v_mov_b32_e32 v58, v183
	v_pk_fma_f32 v[52:53], v[52:53], v[58:59], v[56:57] op_sel_hi:[1,0,1]
	v_pk_fma_f32 v[50:51], v[50:51], v[58:59], v[54:55] op_sel_hi:[1,0,1]
	s_waitcnt lgkmcnt(0)
	v_pk_fma_f32 v[48:49], v[48:49], v[184:185], v[52:53] op_sel_hi:[1,0,1]
	v_pk_fma_f32 v[46:47], v[46:47], v[184:185], v[50:51] op_sel_hi:[1,0,1]
	v_pk_fma_f32 v[44:45], v[44:45], v[184:185], v[48:49] op_sel:[0,1,0]
	v_pk_fma_f32 v[42:43], v[42:43], v[184:185], v[46:47] op_sel:[0,1,0]
	v_pk_fma_f32 v[40:41], v[40:41], v[186:187], v[44:45] op_sel_hi:[1,0,1]
	v_pk_fma_f32 v[38:39], v[38:39], v[186:187], v[42:43] op_sel_hi:[1,0,1]
	v_mov_b32_e32 v42, v187
	s_add_i32 s23, s52, s23
	v_pk_fma_f32 v[36:37], v[36:37], v[42:43], v[40:41] op_sel_hi:[1,0,1]
	v_pk_fma_f32 v[34:35], v[34:35], v[42:43], v[38:39] op_sel_hi:[1,0,1]
	s_cmpk_gt_i32 s23, 0x1ff
	global_store_dwordx4 v[188:189], v[34:37], off offset:1536 nt
	s_cselect_b64 s[14:15], -1, 0
	v_mov_b64_e32 v[40:41], v[28:29]
	v_mov_b64_e32 v[36:37], v[32:33]
	v_mov_b64_e32 v[44:45], v[24:25]
	v_mov_b64_e32 v[48:49], v[20:21]
	v_mov_b64_e32 v[52:53], v[16:17]
	v_mov_b64_e32 v[56:57], v[12:13]
	v_mov_b64_e32 v[60:61], v[8:9]
	v_mov_b64_e32 v[64:65], v[4:5]
	s_and_b64 vcc, exec, s[14:15]
	v_mov_b64_e32 v[34:35], v[30:31]
	v_mov_b64_e32 v[38:39], v[26:27]
	v_mov_b64_e32 v[42:43], v[22:23]
	v_mov_b64_e32 v[46:47], v[18:19]
	v_mov_b64_e32 v[50:51], v[14:15]
	v_mov_b64_e32 v[54:55], v[10:11]
	v_mov_b64_e32 v[58:59], v[6:7]
	v_mov_b64_e32 v[62:63], v[2:3]
	s_cbranch_vccnz .LBB0_451
	v_lshl_add_u64 v[62:63], v[138:139], 0, v[136:137]
	global_load_dwordx4 v[34:37], v[62:63], off nt
	global_load_dwordx4 v[38:41], v[62:63], off offset:512 nt
	global_load_dwordx4 v[42:45], v[62:63], off offset:1024 nt
	global_load_dwordx4 v[46:49], v[62:63], off offset:1536 nt
	global_load_dwordx4 v[50:53], v[62:63], off offset:2048 nt
	global_load_dwordx4 v[54:57], v[62:63], off offset:2560 nt
	global_load_dwordx4 v[58:61], v[62:63], off offset:3072 nt
	s_nop 0
	global_load_dwordx4 v[62:65], v[62:63], off offset:3584 nt
	s_branch .LBB0_451

; __device__ __forceinline__ void hgrn_sample_loop(Frame& F) {
;     const int tid = F.tid;
;     LAS float* Qs = (LAS float*)(F.lds + LX_Q); LAS float* K2 = (LAS float*)(F.lds + LX_K2); LAS float* QT = (LAS float*)(F.lds + LX_QT); LAS float* K3T = (LAS float*)(F.lds + LX_K3T); LAS float* Vs = (LAS float*)(F.lds + LX_V);
;     LAS float* DEC = (LAS float*)(F.lds + LX_DEC); LAS float* ATT = (LAS float*)(F.lds + LX_ATT); LAS float* OP = (LAS float*)(F.lds + LX_OP); LAS float* OT = (LAS float*)(F.lds + LX_OT);
;     const bf16* PB = (const bf16*)(F.ws + WS_PB); const float* FZ = (const float*)(F.ws + WS_FZ); bf16* MIX = (bf16*)(F.ws + WS_MIX);
;     const int v4 = (tid & 31) * 4, kg = tid >> 5;
;     int idx = F.bid; if (idx >= SB_B * HH) return;
;     f32x4 s0[8];
; #pragma unroll
;     for (int j = 0; j < 8; ++j) s0[j] = *(const GAS f32x4*)(F.in[4] + (size_t)idx * HD * HD + (size_t)(8 * kg + j) * HD + v4);
;     for (; idx < SB_B * HH; idx += F.G) {
;         const int b = idx >> 2, h = idx & 3, tok0 = MP + b * SB_T;
;         float* Sout = F.out + O_SHG + (size_t)idx * HD * HD;
;         if (tid < 128) { const int col = h * HD + tid; const float lb = 1.0f / (1.0f + __expf(F.in[5][512 + col] - F.in[5][col]));
;             float gl[8], kk[8], qq[8]; float run = 0.f;
; #pragma unroll
;             for (int t = 0; t < 8; ++t) { const size_t tok = (size_t)(tok0 + t); const float fz = FZ[tok * 512 + col]; qq[t] = bf2f(PB[tok * PBW + 512 + col]);
;                 const float sg = __builtin_amdgcn_rcpf(1.0f + __builtin_amdgcn_exp2f(-1.4426950408889634f * fz)), f = lb + (1.0f - lb) * sg; kk[t] = 1.0f - f; run += __log2f(f); gl[t] = run; }
;             float qt[8], k3[8];
; #pragma unroll
;             for (int t = 0; t < 8; ++t) { qt[t] = qq[t] * __builtin_amdgcn_exp2f(gl[t]); k3[t] = kk[t] * __builtin_amdgcn_exp2f(run - gl[t]); Qs[t * 128 + tid] = qt[t]; K2[t * 128 + tid] = kk[t] * __builtin_amdgcn_exp2f(-gl[t]); }
;             *(LAS f32x4*)(QT + tid * 8) = (f32x4){qt[0], qt[1], qt[2], qt[3]}; *(LAS f32x4*)(QT + tid * 8 + 4) = (f32x4){qt[4], qt[5], qt[6], qt[7]};
;             *(LAS f32x4*)(K3T + tid * 8) = (f32x4){k3[0], k3[1], k3[2], k3[3]}; *(LAS f32x4*)(K3T + tid * 8 + 4) = (f32x4){k3[4], k3[5], k3[6], k3[7]};
;             DEC[tid] = __builtin_amdgcn_exp2f(run);
;         } else if (tid < 256) { const int vv = tid - 128;
; #pragma unroll
.LBB0_538:
	s_cmpk_gt_i32 s2, 0x1ff
	s_cbranch_scc1 .LBB0_551
	s_ashr_i32 s3, s2, 31
	v_readlane_b32 s60, v238, 4
	v_lshrrev_b32_e32 v36, 5, v0
	s_lshl_b64 s[12:13], s[2:3], 16
	v_readlane_b32 s68, v238, 12
	v_lshlrev_b32_e32 v4, 3, v36
	v_mov_b32_e32 v133, 0
	v_readlane_b32 s69, v238, 13
	s_add_u32 s0, s68, s12
	v_lshlrev_b32_e32 v6, 4, v0
	v_or_b32_e32 v37, 1, v4
	v_or_b32_e32 v38, 2, v4
	v_or_b32_e32 v39, 3, v4
	v_or_b32_e32 v40, 4, v4
	v_or_b32_e32 v41, 5, v4
	v_or_b32_e32 v43, 6, v4
	v_or_b32_e32 v44, 7, v4
	s_addc_u32 s1, s69, s13
	v_and_b32_e32 v34, 0x1f0, v6
	v_mov_b32_e32 v35, v133
	v_lshlrev_b32_e32 v130, 12, v36
	v_mov_b32_e32 v131, v133
	v_lshlrev_b32_e32 v132, 9, v37
	s_waitcnt vmcnt(0)
	v_lshlrev_b32_e32 v18, 9, v38
	v_mov_b32_e32 v19, v133
	v_lshlrev_b32_e32 v20, 9, v39
	v_mov_b32_e32 v21, v133
	v_lshlrev_b32_e32 v10, 9, v40
	v_mov_b32_e32 v11, v133
	v_lshlrev_b32_e32 v12, 9, v41
	v_mov_b32_e32 v13, v133
	v_lshlrev_b32_e32 v2, 9, v43
	v_mov_b32_e32 v3, v133
	v_lshlrev_b32_e32 v4, 9, v44
	v_mov_b32_e32 v5, v133
	v_lshl_add_u64 v[26:27], s[0:1], 0, v[34:35]
	v_lshl_add_u64 v[4:5], v[26:27], 0, v[4:5]
	v_lshl_add_u64 v[6:7], v[26:27], 0, v[2:3]
	v_lshl_add_u64 v[12:13], v[26:27], 0, v[12:13]
	v_lshl_add_u64 v[14:15], v[26:27], 0, v[10:11]
	v_lshl_add_u64 v[20:21], v[26:27], 0, v[20:21]
	v_lshl_add_u64 v[22:23], v[26:27], 0, v[18:19]
	v_lshl_add_u64 v[28:29], v[26:27], 0, v[132:133]
	v_lshl_add_u64 v[30:31], v[26:27], 0, v[130:131]
	global_load_dwordx4 v[2:5], v[4:5], off nt
	s_nop 0
	global_load_dwordx4 v[6:9], v[6:7], off nt
	s_nop 0
	global_load_dwordx4 v[10:13], v[12:13], off nt
	s_nop 0
	global_load_dwordx4 v[14:17], v[14:15], off nt
	s_nop 0
	global_load_dwordx4 v[18:21], v[20:21], off nt
	s_nop 0
	global_load_dwordx4 v[22:25], v[22:23], off nt
	s_nop 0
	global_load_dwordx4 v[26:29], v[28:29], off nt
	s_nop 0
	global_load_dwordx4 v[30:33], v[30:31], off nt
	v_and_b32_e32 v35, 7, v0
	v_lshrrev_b32_e32 v46, 6, v0
	v_bfe_u32 v47, v0, 3, 3
	v_lshlrev_b32_e32 v48, 9, v46
	v_lshlrev_b32_e32 v49, 2, v35
	v_add3_u32 v147, 0, v48, v49
	v_lshlrev_b32_e32 v48, 9, v47
	v_add3_u32 v148, 0, v48, v49
	v_mbcnt_lo_u32_b32 v48, -1, 0
	v_mbcnt_hi_u32_b32 v48, -1, v48
	s_movk_i32 s0, 0x80
	v_and_b32_e32 v50, 64, v48
	v_subrev_co_u32_e32 v132, vcc, s0, v0
	v_xor_b32_e32 v49, 1, v48
	v_add_u32_e32 v50, 64, v50
	s_xor_b64 s[4:5], vcc, -1
	v_cmp_lt_i32_e32 vcc, v49, v50
	v_add_u32_e32 v144, 0, v34
	v_lshrrev_b32_e32 v34, 3, v0
	v_cndmask_b32_e32 v49, v48, v49, vcc
	v_lshlrev_b32_e32 v149, 2, v49
	v_xor_b32_e32 v49, 2, v48
	v_cmp_lt_i32_e32 vcc, v49, v50
	v_lshl_add_u32 v152, v34, 2, 0
	v_xor_b32_e32 v34, 8, v48
	v_cndmask_b32_e32 v49, v48, v49, vcc
	v_lshlrev_b32_e32 v150, 2, v49
	v_xor_b32_e32 v49, 4, v48
	v_cmp_lt_i32_e32 vcc, v49, v50
	v_cmp_eq_u32_e64 s[6:7], 0, v35
	v_lshl_add_u32 v153, v42, 2, 0
	v_cndmask_b32_e32 v49, v48, v49, vcc
	v_cmp_lt_i32_e32 vcc, v34, v50
	v_and_b32_e32 v35, 0x180, v0
	v_lshl_add_u32 v166, v35, 2, v153
	v_cndmask_b32_e32 v34, v48, v34, vcc
	v_lshlrev_b32_e32 v155, 2, v34
	v_xor_b32_e32 v34, 16, v48
	v_cmp_lt_i32_e32 vcc, v34, v50
	v_lshrrev_b32_e32 v35, 2, v0
	v_lshl_add_u32 v159, v37, 5, 0
	v_cndmask_b32_e32 v34, v48, v34, vcc
	v_lshlrev_b32_e32 v156, 2, v34
	v_xor_b32_e32 v34, 32, v48
	v_cmp_lt_i32_e32 vcc, v34, v50
	v_and_b32_e32 v37, 0x60, v35
	s_movk_i32 s3, 0x380
	v_mov_b32_e32 v35, 0x200
	s_add_i32 s10, s2, s52
	v_cndmask_b32_e32 v34, v48, v34, vcc
	v_bitop3_b32 v35, v0, s3, v35 bitop3:0xc8
	s_lshl_b32 s3, s96, 9
	s_ashr_i32 s11, s10, 31
	v_lshlrev_b32_e32 v157, 2, v34
	v_or_b32_e32 v34, 0x200, v0
	s_add_i32 s3, s3, 0
	s_lshl_b64 s[10:11], s[10:11], 16
	v_lshrrev_b32_e32 v34, 2, v34
	v_readlane_b32 s16, v238, 29
	s_add_u32 s10, s68, s10
	v_lshl_add_u32 v160, v38, 5, 0
	v_and_b32_e32 v38, 0xe0, v34
	v_lshlrev_b32_e32 v34, 3, v154
	v_readlane_b32 s22, v238, 35
	s_addc_u32 s11, s69, s11
	v_add_u32_e32 v170, s3, v34
	v_lshl_add_u64 v[138:139], s[10:11], 0, v[130:131]
	s_lshl_b64 s[10:11], s[52:53], 16
	s_lshl_b32 s3, s2, 1
	s_lshl_b32 s22, s52, 1
	v_lshl_add_u32 v168, v35, 2, v153
	v_mov_b32_e32 v35, v133
	v_readlane_b32 s18, v238, 31
	v_readlane_b32 s19, v238, 32
	s_add_u32 s12, s48, s12
	v_lshl_add_u32 v145, v0, 2, 0
	v_lshl_add_u64 v[134:135], s[18:19], 0, v[34:35]
	v_and_b32_e32 v34, 31, v0
	s_addc_u32 s13, s49, s13
	s_movk_i32 s0, 0x100
	v_mad_u32_u24 v146, v0, 28, v145
	v_mul_i32_i24_e32 v45, 0xffffffe4, v0
	v_lshl_add_u32 v158, v36, 8, 0
	v_mul_i32_i24_e32 v36, 0xffffff20, v36
	v_readlane_b32 s23, v238, 36
	v_lshlrev_b32_e32 v136, 4, v34
	v_lshl_add_u64 v[34:35], s[12:13], 0, v[130:131]
	s_mov_b64 s[12:13], 0x4820800
	v_cmp_gt_u32_e64 s[0:1], s0, v0
	v_lshlrev_b32_e32 v151, 2, v49
	v_cmp_gt_u32_e64 s[8:9], v47, v46
	v_lshl_add_u32 v161, v39, 5, 0
	v_lshl_add_u32 v162, v40, 5, 0
	v_lshl_add_u32 v163, v41, 5, 0
	v_lshl_add_u32 v164, v43, 5, 0
	v_lshl_add_u32 v165, v44, 5, 0
	v_add_u32_e32 v167, 0x6300, v166
	v_add_u32_e32 v169, 0x6300, v168
	v_mov_b32_e32 v137, v133
	v_lshl_add_u64 v[140:141], v[34:35], 0, s[12:13]
	v_lshlrev_b64 v[142:143], 1, v[132:133]
	v_add_u32_e32 v131, v146, v45
	v_add_u32_e32 v171, v158, v36
	v_add_u32_e32 v172, 0, v37
	v_add_u32_e32 v173, 0, v38
	v_lshlrev_b32_e32 v132, 1, v74
	v_mov_b32_e32 v174, 0x358637bd
	s_mov_b32 s23, s2
	v_readlane_b32 s61, v238, 5
	v_readlane_b32 s62, v238, 6
	v_readlane_b32 s63, v238, 7
	v_readlane_b32 s64, v238, 8
	v_readlane_b32 s65, v238, 9
	v_readlane_b32 s66, v238, 10
	v_readlane_b32 s67, v238, 11
	v_readlane_b32 s70, v238, 14
	v_readlane_b32 s71, v238, 15
	v_readlane_b32 s72, v238, 16
	v_readlane_b32 s73, v238, 17
	v_readlane_b32 s74, v238, 18
	v_readlane_b32 s75, v238, 19
	v_readlane_b32 s17, v238, 30
	v_readlane_b32 s20, v238, 33
	v_readlane_b32 s21, v238, 34
	v_readlane_b32 s24, v238, 37
	v_readlane_b32 s25, v238, 38
	v_readlane_b32 s26, v238, 39
	v_readlane_b32 s27, v238, 40
	v_readlane_b32 s28, v238, 41
	v_readlane_b32 s29, v238, 42
	v_readlane_b32 s30, v238, 43
	v_readlane_b32 s31, v238, 44
	s_branch .LBB0_541
